# adaLN GEMV prefetch ring 64 loads in flight (on top of cmp1 deferral + log1p)
# speedup vs baseline: 1.0097x; 1.0097x over previous
.LBB0_537:
	s_or_b64 exec, exec, s[2:3]
	s_mul_hi_i32 s2, s6, 0x2aaaaaab
	s_lshr_b32 s3, s2, 31
	s_ashr_i32 s4, s2, 3
	s_add_i32 s4, s4, s3
	s_mul_i32 s2, s4, 48
	s_sub_i32 s2, s6, s2
	v_lshl_or_b32 v8, s2, 6, v0
	v_ashrrev_i32_e32 v9, 31, v8
	v_lshlrev_b64 v[10:11], 2, v[8:9]
	v_mad_i64_i32 v[10:11], s[2:3], s4, v211, v[10:11]
	v_mov_b32_e32 v12, 0
	v_lshl_add_u64 v[10:11], v[6:7], 0, v[10:11]
	s_mov_b64 s[2:3], 0
	v_mov_b32_e32 v25, v3
	v_mov_b32_e32 v13, v12
	v_mov_b32_e32 v18, v12
	v_mov_b32_e32 v19, v12
	v_mov_b32_e32 v16, v12
	v_mov_b32_e32 v17, v12
	v_mov_b32_e32 v14, v12
	v_mov_b32_e32 v15, v12
	s_waitcnt lgkmcnt(0)
	s_barrier
	v_mov_b32_e32 v158, 0x3000
	v_mov_b32_e32 v159, 0
	v_mov_b32_e32 v160, 0x6000
	v_mov_b32_e32 v161, 0
	v_mov_b32_e32 v162, 0x9000
	v_mov_b32_e32 v163, 0
	v_mov_b32_e32 v164, 0xc000
	v_mov_b32_e32 v165, 0
	v_mov_b32_e32 v166, v10
	v_mov_b32_e32 v167, v11
	global_load_dword v66, v[166:167], off
	v_lshl_add_u64 v[168:169], v[166:167], 0, v[158:159]
	v_lshl_add_u64 v[170:171], v[166:167], 0, v[160:161]
	v_lshl_add_u64 v[172:173], v[166:167], 0, v[162:163]
	global_load_dword v67, v[168:169], off
	global_load_dword v68, v[170:171], off
	global_load_dword v69, v[172:173], off
	v_lshl_add_u64 v[166:167], v[166:167], 0, v[164:165]
	global_load_dword v70, v[166:167], off
	v_lshl_add_u64 v[168:169], v[166:167], 0, v[158:159]
	v_lshl_add_u64 v[170:171], v[166:167], 0, v[160:161]
	v_lshl_add_u64 v[172:173], v[166:167], 0, v[162:163]
	global_load_dword v71, v[168:169], off
	global_load_dword v72, v[170:171], off
	global_load_dword v73, v[172:173], off
	v_lshl_add_u64 v[166:167], v[166:167], 0, v[164:165]
	global_load_dword v74, v[166:167], off
	v_lshl_add_u64 v[168:169], v[166:167], 0, v[158:159]
	v_lshl_add_u64 v[170:171], v[166:167], 0, v[160:161]
	v_lshl_add_u64 v[172:173], v[166:167], 0, v[162:163]
	global_load_dword v75, v[168:169], off
	global_load_dword v76, v[170:171], off
	global_load_dword v77, v[172:173], off
	v_lshl_add_u64 v[166:167], v[166:167], 0, v[164:165]
	global_load_dword v78, v[166:167], off
	v_lshl_add_u64 v[168:169], v[166:167], 0, v[158:159]
	v_lshl_add_u64 v[170:171], v[166:167], 0, v[160:161]
	v_lshl_add_u64 v[172:173], v[166:167], 0, v[162:163]
	global_load_dword v79, v[168:169], off
	global_load_dword v80, v[170:171], off
	global_load_dword v81, v[172:173], off
	v_lshl_add_u64 v[166:167], v[166:167], 0, v[164:165]
	global_load_dword v82, v[166:167], off
	v_lshl_add_u64 v[168:169], v[166:167], 0, v[158:159]
	v_lshl_add_u64 v[170:171], v[166:167], 0, v[160:161]
	v_lshl_add_u64 v[172:173], v[166:167], 0, v[162:163]
	global_load_dword v83, v[168:169], off
	global_load_dword v84, v[170:171], off
	global_load_dword v85, v[172:173], off
	v_lshl_add_u64 v[166:167], v[166:167], 0, v[164:165]
	global_load_dword v86, v[166:167], off
	v_lshl_add_u64 v[168:169], v[166:167], 0, v[158:159]
	v_lshl_add_u64 v[170:171], v[166:167], 0, v[160:161]
	v_lshl_add_u64 v[172:173], v[166:167], 0, v[162:163]
	global_load_dword v87, v[168:169], off
	global_load_dword v88, v[170:171], off
	global_load_dword v89, v[172:173], off
	v_lshl_add_u64 v[166:167], v[166:167], 0, v[164:165]
	global_load_dword v90, v[166:167], off
	v_lshl_add_u64 v[168:169], v[166:167], 0, v[158:159]
	v_lshl_add_u64 v[170:171], v[166:167], 0, v[160:161]
	v_lshl_add_u64 v[172:173], v[166:167], 0, v[162:163]
	global_load_dword v91, v[168:169], off
	global_load_dword v92, v[170:171], off
	global_load_dword v93, v[172:173], off
	v_lshl_add_u64 v[166:167], v[166:167], 0, v[164:165]
	global_load_dword v94, v[166:167], off
	v_lshl_add_u64 v[168:169], v[166:167], 0, v[158:159]
	v_lshl_add_u64 v[170:171], v[166:167], 0, v[160:161]
	v_lshl_add_u64 v[172:173], v[166:167], 0, v[162:163]
	global_load_dword v95, v[168:169], off
	global_load_dword v96, v[170:171], off
	global_load_dword v97, v[172:173], off
	v_lshl_add_u64 v[166:167], v[166:167], 0, v[164:165]
	global_load_dword v98, v[166:167], off
	v_lshl_add_u64 v[168:169], v[166:167], 0, v[158:159]
	v_lshl_add_u64 v[170:171], v[166:167], 0, v[160:161]
	v_lshl_add_u64 v[172:173], v[166:167], 0, v[162:163]
	global_load_dword v99, v[168:169], off
	global_load_dword v100, v[170:171], off
	global_load_dword v101, v[172:173], off
	v_lshl_add_u64 v[166:167], v[166:167], 0, v[164:165]
	global_load_dword v102, v[166:167], off
	v_lshl_add_u64 v[168:169], v[166:167], 0, v[158:159]
	v_lshl_add_u64 v[170:171], v[166:167], 0, v[160:161]
	v_lshl_add_u64 v[172:173], v[166:167], 0, v[162:163]
	global_load_dword v103, v[168:169], off
	global_load_dword v104, v[170:171], off
	global_load_dword v105, v[172:173], off
	v_lshl_add_u64 v[166:167], v[166:167], 0, v[164:165]
	global_load_dword v106, v[166:167], off
	v_lshl_add_u64 v[168:169], v[166:167], 0, v[158:159]
	v_lshl_add_u64 v[170:171], v[166:167], 0, v[160:161]
	v_lshl_add_u64 v[172:173], v[166:167], 0, v[162:163]
	global_load_dword v107, v[168:169], off
	global_load_dword v108, v[170:171], off
	global_load_dword v109, v[172:173], off
	v_lshl_add_u64 v[166:167], v[166:167], 0, v[164:165]
	global_load_dword v110, v[166:167], off
	v_lshl_add_u64 v[168:169], v[166:167], 0, v[158:159]
	v_lshl_add_u64 v[170:171], v[166:167], 0, v[160:161]
	v_lshl_add_u64 v[172:173], v[166:167], 0, v[162:163]
	global_load_dword v111, v[168:169], off
	global_load_dword v112, v[170:171], off
	global_load_dword v113, v[172:173], off
	v_lshl_add_u64 v[166:167], v[166:167], 0, v[164:165]
	global_load_dword v114, v[166:167], off
	v_lshl_add_u64 v[168:169], v[166:167], 0, v[158:159]
	v_lshl_add_u64 v[170:171], v[166:167], 0, v[160:161]
	v_lshl_add_u64 v[172:173], v[166:167], 0, v[162:163]
	global_load_dword v115, v[168:169], off
	global_load_dword v116, v[170:171], off
	global_load_dword v117, v[172:173], off
	v_lshl_add_u64 v[166:167], v[166:167], 0, v[164:165]
	global_load_dword v118, v[166:167], off
	v_lshl_add_u64 v[168:169], v[166:167], 0, v[158:159]
	v_lshl_add_u64 v[170:171], v[166:167], 0, v[160:161]
	v_lshl_add_u64 v[172:173], v[166:167], 0, v[162:163]
	global_load_dword v119, v[168:169], off
	global_load_dword v120, v[170:171], off
	global_load_dword v121, v[172:173], off
	v_lshl_add_u64 v[166:167], v[166:167], 0, v[164:165]
	global_load_dword v122, v[166:167], off
	v_lshl_add_u64 v[168:169], v[166:167], 0, v[158:159]
	v_lshl_add_u64 v[170:171], v[166:167], 0, v[160:161]
	v_lshl_add_u64 v[172:173], v[166:167], 0, v[162:163]
	global_load_dword v123, v[168:169], off
	global_load_dword v124, v[170:171], off
	global_load_dword v125, v[172:173], off
	v_lshl_add_u64 v[166:167], v[166:167], 0, v[164:165]
	global_load_dword v126, v[166:167], off
	v_lshl_add_u64 v[168:169], v[166:167], 0, v[158:159]
	v_lshl_add_u64 v[170:171], v[166:167], 0, v[160:161]
	v_lshl_add_u64 v[172:173], v[166:167], 0, v[162:163]
	global_load_dword v127, v[168:169], off
	global_load_dword v128, v[170:171], off
	global_load_dword v129, v[172:173], off
	v_lshl_add_u64 v[166:167], v[166:167], 0, v[164:165]
	s_mov_b32 s2, 3
.Lada_loop:
	ds_read_b128 v[26:29], v25
	ds_read_b128 v[30:33], v25 offset:4096
	ds_read_b128 v[34:37], v25 offset:8192
	ds_read_b128 v[38:41], v25 offset:12288
	ds_read_b128 v[42:45], v25 offset:16384
	ds_read_b128 v[46:49], v25 offset:20480
	ds_read_b128 v[50:53], v25 offset:24576
	ds_read_b128 v[54:57], v25 offset:28672
	v_add_u32_e32 v25, 16, v25
	s_waitcnt vmcnt(60)
	s_waitcnt lgkmcnt(0)
	v_fmac_f32_e32 v18, v66, v26
	v_fmac_f32_e32 v19, v66, v30
	v_fmac_f32_e32 v16, v66, v34
	v_fmac_f32_e32 v17, v66, v38
	v_fmac_f32_e32 v14, v66, v42
	v_fmac_f32_e32 v15, v66, v46
	v_fmac_f32_e32 v12, v66, v50
	v_fmac_f32_e32 v13, v66, v54
	v_fmac_f32_e32 v18, v67, v27
	v_fmac_f32_e32 v19, v67, v31
	v_fmac_f32_e32 v16, v67, v35
	v_fmac_f32_e32 v17, v67, v39
	v_fmac_f32_e32 v14, v67, v43
	v_fmac_f32_e32 v15, v67, v47
	v_fmac_f32_e32 v12, v67, v51
	v_fmac_f32_e32 v13, v67, v55
	v_fmac_f32_e32 v18, v68, v28
	v_fmac_f32_e32 v19, v68, v32
	v_fmac_f32_e32 v16, v68, v36
	v_fmac_f32_e32 v17, v68, v40
	v_fmac_f32_e32 v14, v68, v44
	v_fmac_f32_e32 v15, v68, v48
	v_fmac_f32_e32 v12, v68, v52
	v_fmac_f32_e32 v13, v68, v56
	v_fmac_f32_e32 v18, v69, v29
	v_fmac_f32_e32 v19, v69, v33
	v_fmac_f32_e32 v16, v69, v37
	v_fmac_f32_e32 v17, v69, v41
	v_fmac_f32_e32 v14, v69, v45
	v_fmac_f32_e32 v15, v69, v49
	v_fmac_f32_e32 v12, v69, v53
	v_fmac_f32_e32 v13, v69, v57
	global_load_dword v66, v[166:167], off
	v_lshl_add_u64 v[168:169], v[166:167], 0, v[158:159]
	v_lshl_add_u64 v[170:171], v[166:167], 0, v[160:161]
	v_lshl_add_u64 v[172:173], v[166:167], 0, v[162:163]
	global_load_dword v67, v[168:169], off
	global_load_dword v68, v[170:171], off
	global_load_dword v69, v[172:173], off
	v_lshl_add_u64 v[166:167], v[166:167], 0, v[164:165]
	ds_read_b128 v[26:29], v25
	ds_read_b128 v[30:33], v25 offset:4096
	ds_read_b128 v[34:37], v25 offset:8192
	ds_read_b128 v[38:41], v25 offset:12288
	ds_read_b128 v[42:45], v25 offset:16384
	ds_read_b128 v[46:49], v25 offset:20480
	ds_read_b128 v[50:53], v25 offset:24576
	ds_read_b128 v[54:57], v25 offset:28672
	v_add_u32_e32 v25, 16, v25
	s_waitcnt vmcnt(60)
	s_waitcnt lgkmcnt(0)
	v_fmac_f32_e32 v18, v70, v26
	v_fmac_f32_e32 v19, v70, v30
	v_fmac_f32_e32 v16, v70, v34
	v_fmac_f32_e32 v17, v70, v38
	v_fmac_f32_e32 v14, v70, v42
	v_fmac_f32_e32 v15, v70, v46
	v_fmac_f32_e32 v12, v70, v50
	v_fmac_f32_e32 v13, v70, v54
	v_fmac_f32_e32 v18, v71, v27
	v_fmac_f32_e32 v19, v71, v31
	v_fmac_f32_e32 v16, v71, v35
	v_fmac_f32_e32 v17, v71, v39
	v_fmac_f32_e32 v14, v71, v43
	v_fmac_f32_e32 v15, v71, v47
	v_fmac_f32_e32 v12, v71, v51
	v_fmac_f32_e32 v13, v71, v55
	v_fmac_f32_e32 v18, v72, v28
	v_fmac_f32_e32 v19, v72, v32
	v_fmac_f32_e32 v16, v72, v36
	v_fmac_f32_e32 v17, v72, v40
	v_fmac_f32_e32 v14, v72, v44
	v_fmac_f32_e32 v15, v72, v48
	v_fmac_f32_e32 v12, v72, v52
	v_fmac_f32_e32 v13, v72, v56
	v_fmac_f32_e32 v18, v73, v29
	v_fmac_f32_e32 v19, v73, v33
	v_fmac_f32_e32 v16, v73, v37
	v_fmac_f32_e32 v17, v73, v41
	v_fmac_f32_e32 v14, v73, v45
	v_fmac_f32_e32 v15, v73, v49
	v_fmac_f32_e32 v12, v73, v53
	v_fmac_f32_e32 v13, v73, v57
	global_load_dword v70, v[166:167], off
	v_lshl_add_u64 v[168:169], v[166:167], 0, v[158:159]
	v_lshl_add_u64 v[170:171], v[166:167], 0, v[160:161]
	v_lshl_add_u64 v[172:173], v[166:167], 0, v[162:163]
	global_load_dword v71, v[168:169], off
	global_load_dword v72, v[170:171], off
	global_load_dword v73, v[172:173], off
	v_lshl_add_u64 v[166:167], v[166:167], 0, v[164:165]
	ds_read_b128 v[26:29], v25
	ds_read_b128 v[30:33], v25 offset:4096
	ds_read_b128 v[34:37], v25 offset:8192
	ds_read_b128 v[38:41], v25 offset:12288
	ds_read_b128 v[42:45], v25 offset:16384
	ds_read_b128 v[46:49], v25 offset:20480
	ds_read_b128 v[50:53], v25 offset:24576
	ds_read_b128 v[54:57], v25 offset:28672
	v_add_u32_e32 v25, 16, v25
	s_waitcnt vmcnt(60)
	s_waitcnt lgkmcnt(0)
	v_fmac_f32_e32 v18, v74, v26
	v_fmac_f32_e32 v19, v74, v30
	v_fmac_f32_e32 v16, v74, v34
	v_fmac_f32_e32 v17, v74, v38
	v_fmac_f32_e32 v14, v74, v42
	v_fmac_f32_e32 v15, v74, v46
	v_fmac_f32_e32 v12, v74, v50
	v_fmac_f32_e32 v13, v74, v54
	v_fmac_f32_e32 v18, v75, v27
	v_fmac_f32_e32 v19, v75, v31
	v_fmac_f32_e32 v16, v75, v35
	v_fmac_f32_e32 v17, v75, v39
	v_fmac_f32_e32 v14, v75, v43
	v_fmac_f32_e32 v15, v75, v47
	v_fmac_f32_e32 v12, v75, v51
	v_fmac_f32_e32 v13, v75, v55
	v_fmac_f32_e32 v18, v76, v28
	v_fmac_f32_e32 v19, v76, v32
	v_fmac_f32_e32 v16, v76, v36
	v_fmac_f32_e32 v17, v76, v40
	v_fmac_f32_e32 v14, v76, v44
	v_fmac_f32_e32 v15, v76, v48
	v_fmac_f32_e32 v12, v76, v52
	v_fmac_f32_e32 v13, v76, v56
	v_fmac_f32_e32 v18, v77, v29
	v_fmac_f32_e32 v19, v77, v33
	v_fmac_f32_e32 v16, v77, v37
	v_fmac_f32_e32 v17, v77, v41
	v_fmac_f32_e32 v14, v77, v45
	v_fmac_f32_e32 v15, v77, v49
	v_fmac_f32_e32 v12, v77, v53
	v_fmac_f32_e32 v13, v77, v57
	global_load_dword v74, v[166:167], off
	v_lshl_add_u64 v[168:169], v[166:167], 0, v[158:159]
	v_lshl_add_u64 v[170:171], v[166:167], 0, v[160:161]
	v_lshl_add_u64 v[172:173], v[166:167], 0, v[162:163]
	global_load_dword v75, v[168:169], off
	global_load_dword v76, v[170:171], off
	global_load_dword v77, v[172:173], off
	v_lshl_add_u64 v[166:167], v[166:167], 0, v[164:165]
	ds_read_b128 v[26:29], v25
	ds_read_b128 v[30:33], v25 offset:4096
	ds_read_b128 v[34:37], v25 offset:8192
	ds_read_b128 v[38:41], v25 offset:12288
	ds_read_b128 v[42:45], v25 offset:16384
	ds_read_b128 v[46:49], v25 offset:20480
	ds_read_b128 v[50:53], v25 offset:24576
	ds_read_b128 v[54:57], v25 offset:28672
	v_add_u32_e32 v25, 16, v25
	s_waitcnt vmcnt(60)
	s_waitcnt lgkmcnt(0)
	v_fmac_f32_e32 v18, v78, v26
	v_fmac_f32_e32 v19, v78, v30
	v_fmac_f32_e32 v16, v78, v34
	v_fmac_f32_e32 v17, v78, v38
	v_fmac_f32_e32 v14, v78, v42
	v_fmac_f32_e32 v15, v78, v46
	v_fmac_f32_e32 v12, v78, v50
	v_fmac_f32_e32 v13, v78, v54
	v_fmac_f32_e32 v18, v79, v27
	v_fmac_f32_e32 v19, v79, v31
	v_fmac_f32_e32 v16, v79, v35
	v_fmac_f32_e32 v17, v79, v39
	v_fmac_f32_e32 v14, v79, v43
	v_fmac_f32_e32 v15, v79, v47
	v_fmac_f32_e32 v12, v79, v51
	v_fmac_f32_e32 v13, v79, v55
	v_fmac_f32_e32 v18, v80, v28
	v_fmac_f32_e32 v19, v80, v32
	v_fmac_f32_e32 v16, v80, v36
	v_fmac_f32_e32 v17, v80, v40
	v_fmac_f32_e32 v14, v80, v44
	v_fmac_f32_e32 v15, v80, v48
	v_fmac_f32_e32 v12, v80, v52
	v_fmac_f32_e32 v13, v80, v56
	v_fmac_f32_e32 v18, v81, v29
	v_fmac_f32_e32 v19, v81, v33
	v_fmac_f32_e32 v16, v81, v37
	v_fmac_f32_e32 v17, v81, v41
	v_fmac_f32_e32 v14, v81, v45
	v_fmac_f32_e32 v15, v81, v49
	v_fmac_f32_e32 v12, v81, v53
	v_fmac_f32_e32 v13, v81, v57
	global_load_dword v78, v[166:167], off
	v_lshl_add_u64 v[168:169], v[166:167], 0, v[158:159]
	v_lshl_add_u64 v[170:171], v[166:167], 0, v[160:161]
	v_lshl_add_u64 v[172:173], v[166:167], 0, v[162:163]
	global_load_dword v79, v[168:169], off
	global_load_dword v80, v[170:171], off
	global_load_dword v81, v[172:173], off
	v_lshl_add_u64 v[166:167], v[166:167], 0, v[164:165]
	ds_read_b128 v[26:29], v25
	ds_read_b128 v[30:33], v25 offset:4096
	ds_read_b128 v[34:37], v25 offset:8192
	ds_read_b128 v[38:41], v25 offset:12288
	ds_read_b128 v[42:45], v25 offset:16384
	ds_read_b128 v[46:49], v25 offset:20480
	ds_read_b128 v[50:53], v25 offset:24576
	ds_read_b128 v[54:57], v25 offset:28672
	v_add_u32_e32 v25, 16, v25
	s_waitcnt vmcnt(60)
	s_waitcnt lgkmcnt(0)
	v_fmac_f32_e32 v18, v82, v26
	v_fmac_f32_e32 v19, v82, v30
	v_fmac_f32_e32 v16, v82, v34
	v_fmac_f32_e32 v17, v82, v38
	v_fmac_f32_e32 v14, v82, v42
	v_fmac_f32_e32 v15, v82, v46
	v_fmac_f32_e32 v12, v82, v50
	v_fmac_f32_e32 v13, v82, v54
	v_fmac_f32_e32 v18, v83, v27
	v_fmac_f32_e32 v19, v83, v31
	v_fmac_f32_e32 v16, v83, v35
	v_fmac_f32_e32 v17, v83, v39
	v_fmac_f32_e32 v14, v83, v43
	v_fmac_f32_e32 v15, v83, v47
	v_fmac_f32_e32 v12, v83, v51
	v_fmac_f32_e32 v13, v83, v55
	v_fmac_f32_e32 v18, v84, v28
	v_fmac_f32_e32 v19, v84, v32
	v_fmac_f32_e32 v16, v84, v36
	v_fmac_f32_e32 v17, v84, v40
	v_fmac_f32_e32 v14, v84, v44
	v_fmac_f32_e32 v15, v84, v48
	v_fmac_f32_e32 v12, v84, v52
	v_fmac_f32_e32 v13, v84, v56
	v_fmac_f32_e32 v18, v85, v29
	v_fmac_f32_e32 v19, v85, v33
	v_fmac_f32_e32 v16, v85, v37
	v_fmac_f32_e32 v17, v85, v41
	v_fmac_f32_e32 v14, v85, v45
	v_fmac_f32_e32 v15, v85, v49
	v_fmac_f32_e32 v12, v85, v53
	v_fmac_f32_e32 v13, v85, v57
	global_load_dword v82, v[166:167], off
	v_lshl_add_u64 v[168:169], v[166:167], 0, v[158:159]
	v_lshl_add_u64 v[170:171], v[166:167], 0, v[160:161]
	v_lshl_add_u64 v[172:173], v[166:167], 0, v[162:163]
	global_load_dword v83, v[168:169], off
	global_load_dword v84, v[170:171], off
	global_load_dword v85, v[172:173], off
	v_lshl_add_u64 v[166:167], v[166:167], 0, v[164:165]
	ds_read_b128 v[26:29], v25
	ds_read_b128 v[30:33], v25 offset:4096
	ds_read_b128 v[34:37], v25 offset:8192
	ds_read_b128 v[38:41], v25 offset:12288
	ds_read_b128 v[42:45], v25 offset:16384
	ds_read_b128 v[46:49], v25 offset:20480
	ds_read_b128 v[50:53], v25 offset:24576
	ds_read_b128 v[54:57], v25 offset:28672
	v_add_u32_e32 v25, 16, v25
	s_waitcnt vmcnt(60)
	s_waitcnt lgkmcnt(0)
	v_fmac_f32_e32 v18, v86, v26
	v_fmac_f32_e32 v19, v86, v30
	v_fmac_f32_e32 v16, v86, v34
	v_fmac_f32_e32 v17, v86, v38
	v_fmac_f32_e32 v14, v86, v42
	v_fmac_f32_e32 v15, v86, v46
	v_fmac_f32_e32 v12, v86, v50
	v_fmac_f32_e32 v13, v86, v54
	v_fmac_f32_e32 v18, v87, v27
	v_fmac_f32_e32 v19, v87, v31
	v_fmac_f32_e32 v16, v87, v35
	v_fmac_f32_e32 v17, v87, v39
	v_fmac_f32_e32 v14, v87, v43
	v_fmac_f32_e32 v15, v87, v47
	v_fmac_f32_e32 v12, v87, v51
	v_fmac_f32_e32 v13, v87, v55
	v_fmac_f32_e32 v18, v88, v28
	v_fmac_f32_e32 v19, v88, v32
	v_fmac_f32_e32 v16, v88, v36
	v_fmac_f32_e32 v17, v88, v40
	v_fmac_f32_e32 v14, v88, v44
	v_fmac_f32_e32 v15, v88, v48
	v_fmac_f32_e32 v12, v88, v52
	v_fmac_f32_e32 v13, v88, v56
	v_fmac_f32_e32 v18, v89, v29
	v_fmac_f32_e32 v19, v89, v33
	v_fmac_f32_e32 v16, v89, v37
	v_fmac_f32_e32 v17, v89, v41
	v_fmac_f32_e32 v14, v89, v45
	v_fmac_f32_e32 v15, v89, v49
	v_fmac_f32_e32 v12, v89, v53
	v_fmac_f32_e32 v13, v89, v57
	global_load_dword v86, v[166:167], off
	v_lshl_add_u64 v[168:169], v[166:167], 0, v[158:159]
	v_lshl_add_u64 v[170:171], v[166:167], 0, v[160:161]
	v_lshl_add_u64 v[172:173], v[166:167], 0, v[162:163]
	global_load_dword v87, v[168:169], off
	global_load_dword v88, v[170:171], off
	global_load_dword v89, v[172:173], off
	v_lshl_add_u64 v[166:167], v[166:167], 0, v[164:165]
	ds_read_b128 v[26:29], v25
	ds_read_b128 v[30:33], v25 offset:4096
	ds_read_b128 v[34:37], v25 offset:8192
	ds_read_b128 v[38:41], v25 offset:12288
	ds_read_b128 v[42:45], v25 offset:16384
	ds_read_b128 v[46:49], v25 offset:20480
	ds_read_b128 v[50:53], v25 offset:24576
	ds_read_b128 v[54:57], v25 offset:28672
	v_add_u32_e32 v25, 16, v25
	s_waitcnt vmcnt(60)
	s_waitcnt lgkmcnt(0)
	v_fmac_f32_e32 v18, v90, v26
	v_fmac_f32_e32 v19, v90, v30
	v_fmac_f32_e32 v16, v90, v34
	v_fmac_f32_e32 v17, v90, v38
	v_fmac_f32_e32 v14, v90, v42
	v_fmac_f32_e32 v15, v90, v46
	v_fmac_f32_e32 v12, v90, v50
	v_fmac_f32_e32 v13, v90, v54
	v_fmac_f32_e32 v18, v91, v27
	v_fmac_f32_e32 v19, v91, v31
	v_fmac_f32_e32 v16, v91, v35
	v_fmac_f32_e32 v17, v91, v39
	v_fmac_f32_e32 v14, v91, v43
	v_fmac_f32_e32 v15, v91, v47
	v_fmac_f32_e32 v12, v91, v51
	v_fmac_f32_e32 v13, v91, v55
	v_fmac_f32_e32 v18, v92, v28
	v_fmac_f32_e32 v19, v92, v32
	v_fmac_f32_e32 v16, v92, v36
	v_fmac_f32_e32 v17, v92, v40
	v_fmac_f32_e32 v14, v92, v44
	v_fmac_f32_e32 v15, v92, v48
	v_fmac_f32_e32 v12, v92, v52
	v_fmac_f32_e32 v13, v92, v56
	v_fmac_f32_e32 v18, v93, v29
	v_fmac_f32_e32 v19, v93, v33
	v_fmac_f32_e32 v16, v93, v37
	v_fmac_f32_e32 v17, v93, v41
	v_fmac_f32_e32 v14, v93, v45
	v_fmac_f32_e32 v15, v93, v49
	v_fmac_f32_e32 v12, v93, v53
	v_fmac_f32_e32 v13, v93, v57
	global_load_dword v90, v[166:167], off
	v_lshl_add_u64 v[168:169], v[166:167], 0, v[158:159]
	v_lshl_add_u64 v[170:171], v[166:167], 0, v[160:161]
	v_lshl_add_u64 v[172:173], v[166:167], 0, v[162:163]
	global_load_dword v91, v[168:169], off
	global_load_dword v92, v[170:171], off
	global_load_dword v93, v[172:173], off
	v_lshl_add_u64 v[166:167], v[166:167], 0, v[164:165]
	ds_read_b128 v[26:29], v25
	ds_read_b128 v[30:33], v25 offset:4096
	ds_read_b128 v[34:37], v25 offset:8192
	ds_read_b128 v[38:41], v25 offset:12288
	ds_read_b128 v[42:45], v25 offset:16384
	ds_read_b128 v[46:49], v25 offset:20480
	ds_read_b128 v[50:53], v25 offset:24576
	ds_read_b128 v[54:57], v25 offset:28672
	v_add_u32_e32 v25, 16, v25
	s_waitcnt vmcnt(60)
	s_waitcnt lgkmcnt(0)
	v_fmac_f32_e32 v18, v94, v26
	v_fmac_f32_e32 v19, v94, v30
	v_fmac_f32_e32 v16, v94, v34
	v_fmac_f32_e32 v17, v94, v38
	v_fmac_f32_e32 v14, v94, v42
	v_fmac_f32_e32 v15, v94, v46
	v_fmac_f32_e32 v12, v94, v50
	v_fmac_f32_e32 v13, v94, v54
	v_fmac_f32_e32 v18, v95, v27
	v_fmac_f32_e32 v19, v95, v31
	v_fmac_f32_e32 v16, v95, v35
	v_fmac_f32_e32 v17, v95, v39
	v_fmac_f32_e32 v14, v95, v43
	v_fmac_f32_e32 v15, v95, v47
	v_fmac_f32_e32 v12, v95, v51
	v_fmac_f32_e32 v13, v95, v55
	v_fmac_f32_e32 v18, v96, v28
	v_fmac_f32_e32 v19, v96, v32
	v_fmac_f32_e32 v16, v96, v36
	v_fmac_f32_e32 v17, v96, v40
	v_fmac_f32_e32 v14, v96, v44
	v_fmac_f32_e32 v15, v96, v48
	v_fmac_f32_e32 v12, v96, v52
	v_fmac_f32_e32 v13, v96, v56
	v_fmac_f32_e32 v18, v97, v29
	v_fmac_f32_e32 v19, v97, v33
	v_fmac_f32_e32 v16, v97, v37
	v_fmac_f32_e32 v17, v97, v41
	v_fmac_f32_e32 v14, v97, v45
	v_fmac_f32_e32 v15, v97, v49
	v_fmac_f32_e32 v12, v97, v53
	v_fmac_f32_e32 v13, v97, v57
	global_load_dword v94, v[166:167], off
	v_lshl_add_u64 v[168:169], v[166:167], 0, v[158:159]
	v_lshl_add_u64 v[170:171], v[166:167], 0, v[160:161]
	v_lshl_add_u64 v[172:173], v[166:167], 0, v[162:163]
	global_load_dword v95, v[168:169], off
	global_load_dword v96, v[170:171], off
	global_load_dword v97, v[172:173], off
	v_lshl_add_u64 v[166:167], v[166:167], 0, v[164:165]
	ds_read_b128 v[26:29], v25
	ds_read_b128 v[30:33], v25 offset:4096
	ds_read_b128 v[34:37], v25 offset:8192
	ds_read_b128 v[38:41], v25 offset:12288
	ds_read_b128 v[42:45], v25 offset:16384
	ds_read_b128 v[46:49], v25 offset:20480
	ds_read_b128 v[50:53], v25 offset:24576
	ds_read_b128 v[54:57], v25 offset:28672
	v_add_u32_e32 v25, 16, v25
	s_waitcnt vmcnt(60)
	s_waitcnt lgkmcnt(0)
	v_fmac_f32_e32 v18, v98, v26
	v_fmac_f32_e32 v19, v98, v30
	v_fmac_f32_e32 v16, v98, v34
	v_fmac_f32_e32 v17, v98, v38
	v_fmac_f32_e32 v14, v98, v42
	v_fmac_f32_e32 v15, v98, v46
	v_fmac_f32_e32 v12, v98, v50
	v_fmac_f32_e32 v13, v98, v54
	v_fmac_f32_e32 v18, v99, v27
	v_fmac_f32_e32 v19, v99, v31
	v_fmac_f32_e32 v16, v99, v35
	v_fmac_f32_e32 v17, v99, v39
	v_fmac_f32_e32 v14, v99, v43
	v_fmac_f32_e32 v15, v99, v47
	v_fmac_f32_e32 v12, v99, v51
	v_fmac_f32_e32 v13, v99, v55
	v_fmac_f32_e32 v18, v100, v28
	v_fmac_f32_e32 v19, v100, v32
	v_fmac_f32_e32 v16, v100, v36
	v_fmac_f32_e32 v17, v100, v40
	v_fmac_f32_e32 v14, v100, v44
	v_fmac_f32_e32 v15, v100, v48
	v_fmac_f32_e32 v12, v100, v52
	v_fmac_f32_e32 v13, v100, v56
	v_fmac_f32_e32 v18, v101, v29
	v_fmac_f32_e32 v19, v101, v33
	v_fmac_f32_e32 v16, v101, v37
	v_fmac_f32_e32 v17, v101, v41
	v_fmac_f32_e32 v14, v101, v45
	v_fmac_f32_e32 v15, v101, v49
	v_fmac_f32_e32 v12, v101, v53
	v_fmac_f32_e32 v13, v101, v57
	global_load_dword v98, v[166:167], off
	v_lshl_add_u64 v[168:169], v[166:167], 0, v[158:159]
	v_lshl_add_u64 v[170:171], v[166:167], 0, v[160:161]
	v_lshl_add_u64 v[172:173], v[166:167], 0, v[162:163]
	global_load_dword v99, v[168:169], off
	global_load_dword v100, v[170:171], off
	global_load_dword v101, v[172:173], off
	v_lshl_add_u64 v[166:167], v[166:167], 0, v[164:165]
	ds_read_b128 v[26:29], v25
	ds_read_b128 v[30:33], v25 offset:4096
	ds_read_b128 v[34:37], v25 offset:8192
	ds_read_b128 v[38:41], v25 offset:12288
	ds_read_b128 v[42:45], v25 offset:16384
	ds_read_b128 v[46:49], v25 offset:20480
	ds_read_b128 v[50:53], v25 offset:24576
	ds_read_b128 v[54:57], v25 offset:28672
	v_add_u32_e32 v25, 16, v25
	s_waitcnt vmcnt(60)
	s_waitcnt lgkmcnt(0)
	v_fmac_f32_e32 v18, v102, v26
	v_fmac_f32_e32 v19, v102, v30
	v_fmac_f32_e32 v16, v102, v34
	v_fmac_f32_e32 v17, v102, v38
	v_fmac_f32_e32 v14, v102, v42
	v_fmac_f32_e32 v15, v102, v46
	v_fmac_f32_e32 v12, v102, v50
	v_fmac_f32_e32 v13, v102, v54
	v_fmac_f32_e32 v18, v103, v27
	v_fmac_f32_e32 v19, v103, v31
	v_fmac_f32_e32 v16, v103, v35
	v_fmac_f32_e32 v17, v103, v39
	v_fmac_f32_e32 v14, v103, v43
	v_fmac_f32_e32 v15, v103, v47
	v_fmac_f32_e32 v12, v103, v51
	v_fmac_f32_e32 v13, v103, v55
	v_fmac_f32_e32 v18, v104, v28
	v_fmac_f32_e32 v19, v104, v32
	v_fmac_f32_e32 v16, v104, v36
	v_fmac_f32_e32 v17, v104, v40
	v_fmac_f32_e32 v14, v104, v44
	v_fmac_f32_e32 v15, v104, v48
	v_fmac_f32_e32 v12, v104, v52
	v_fmac_f32_e32 v13, v104, v56
	v_fmac_f32_e32 v18, v105, v29
	v_fmac_f32_e32 v19, v105, v33
	v_fmac_f32_e32 v16, v105, v37
	v_fmac_f32_e32 v17, v105, v41
	v_fmac_f32_e32 v14, v105, v45
	v_fmac_f32_e32 v15, v105, v49
	v_fmac_f32_e32 v12, v105, v53
	v_fmac_f32_e32 v13, v105, v57
	global_load_dword v102, v[166:167], off
	v_lshl_add_u64 v[168:169], v[166:167], 0, v[158:159]
	v_lshl_add_u64 v[170:171], v[166:167], 0, v[160:161]
	v_lshl_add_u64 v[172:173], v[166:167], 0, v[162:163]
	global_load_dword v103, v[168:169], off
	global_load_dword v104, v[170:171], off
	global_load_dword v105, v[172:173], off
	v_lshl_add_u64 v[166:167], v[166:167], 0, v[164:165]
	ds_read_b128 v[26:29], v25
	ds_read_b128 v[30:33], v25 offset:4096
	ds_read_b128 v[34:37], v25 offset:8192
	ds_read_b128 v[38:41], v25 offset:12288
	ds_read_b128 v[42:45], v25 offset:16384
	ds_read_b128 v[46:49], v25 offset:20480
	ds_read_b128 v[50:53], v25 offset:24576
	ds_read_b128 v[54:57], v25 offset:28672
	v_add_u32_e32 v25, 16, v25
	s_waitcnt vmcnt(60)
	s_waitcnt lgkmcnt(0)
	v_fmac_f32_e32 v18, v106, v26
	v_fmac_f32_e32 v19, v106, v30
	v_fmac_f32_e32 v16, v106, v34
	v_fmac_f32_e32 v17, v106, v38
	v_fmac_f32_e32 v14, v106, v42
	v_fmac_f32_e32 v15, v106, v46
	v_fmac_f32_e32 v12, v106, v50
	v_fmac_f32_e32 v13, v106, v54
	v_fmac_f32_e32 v18, v107, v27
	v_fmac_f32_e32 v19, v107, v31
	v_fmac_f32_e32 v16, v107, v35
	v_fmac_f32_e32 v17, v107, v39
	v_fmac_f32_e32 v14, v107, v43
	v_fmac_f32_e32 v15, v107, v47
	v_fmac_f32_e32 v12, v107, v51
	v_fmac_f32_e32 v13, v107, v55
	v_fmac_f32_e32 v18, v108, v28
	v_fmac_f32_e32 v19, v108, v32
	v_fmac_f32_e32 v16, v108, v36
	v_fmac_f32_e32 v17, v108, v40
	v_fmac_f32_e32 v14, v108, v44
	v_fmac_f32_e32 v15, v108, v48
	v_fmac_f32_e32 v12, v108, v52
	v_fmac_f32_e32 v13, v108, v56
	v_fmac_f32_e32 v18, v109, v29
	v_fmac_f32_e32 v19, v109, v33
	v_fmac_f32_e32 v16, v109, v37
	v_fmac_f32_e32 v17, v109, v41
	v_fmac_f32_e32 v14, v109, v45
	v_fmac_f32_e32 v15, v109, v49
	v_fmac_f32_e32 v12, v109, v53
	v_fmac_f32_e32 v13, v109, v57
	global_load_dword v106, v[166:167], off
	v_lshl_add_u64 v[168:169], v[166:167], 0, v[158:159]
	v_lshl_add_u64 v[170:171], v[166:167], 0, v[160:161]
	v_lshl_add_u64 v[172:173], v[166:167], 0, v[162:163]
	global_load_dword v107, v[168:169], off
	global_load_dword v108, v[170:171], off
	global_load_dword v109, v[172:173], off
	v_lshl_add_u64 v[166:167], v[166:167], 0, v[164:165]
	ds_read_b128 v[26:29], v25
	ds_read_b128 v[30:33], v25 offset:4096
	ds_read_b128 v[34:37], v25 offset:8192
	ds_read_b128 v[38:41], v25 offset:12288
	ds_read_b128 v[42:45], v25 offset:16384
	ds_read_b128 v[46:49], v25 offset:20480
	ds_read_b128 v[50:53], v25 offset:24576
	ds_read_b128 v[54:57], v25 offset:28672
	v_add_u32_e32 v25, 16, v25
	s_waitcnt vmcnt(60)
	s_waitcnt lgkmcnt(0)
	v_fmac_f32_e32 v18, v110, v26
	v_fmac_f32_e32 v19, v110, v30
	v_fmac_f32_e32 v16, v110, v34
	v_fmac_f32_e32 v17, v110, v38
	v_fmac_f32_e32 v14, v110, v42
	v_fmac_f32_e32 v15, v110, v46
	v_fmac_f32_e32 v12, v110, v50
	v_fmac_f32_e32 v13, v110, v54
	v_fmac_f32_e32 v18, v111, v27
	v_fmac_f32_e32 v19, v111, v31
	v_fmac_f32_e32 v16, v111, v35
	v_fmac_f32_e32 v17, v111, v39
	v_fmac_f32_e32 v14, v111, v43
	v_fmac_f32_e32 v15, v111, v47
	v_fmac_f32_e32 v12, v111, v51
	v_fmac_f32_e32 v13, v111, v55
	v_fmac_f32_e32 v18, v112, v28
	v_fmac_f32_e32 v19, v112, v32
	v_fmac_f32_e32 v16, v112, v36
	v_fmac_f32_e32 v17, v112, v40
	v_fmac_f32_e32 v14, v112, v44
	v_fmac_f32_e32 v15, v112, v48
	v_fmac_f32_e32 v12, v112, v52
	v_fmac_f32_e32 v13, v112, v56
	v_fmac_f32_e32 v18, v113, v29
	v_fmac_f32_e32 v19, v113, v33
	v_fmac_f32_e32 v16, v113, v37
	v_fmac_f32_e32 v17, v113, v41
	v_fmac_f32_e32 v14, v113, v45
	v_fmac_f32_e32 v15, v113, v49
	v_fmac_f32_e32 v12, v113, v53
	v_fmac_f32_e32 v13, v113, v57
	global_load_dword v110, v[166:167], off
	v_lshl_add_u64 v[168:169], v[166:167], 0, v[158:159]
	v_lshl_add_u64 v[170:171], v[166:167], 0, v[160:161]
	v_lshl_add_u64 v[172:173], v[166:167], 0, v[162:163]
	global_load_dword v111, v[168:169], off
	global_load_dword v112, v[170:171], off
	global_load_dword v113, v[172:173], off
	v_lshl_add_u64 v[166:167], v[166:167], 0, v[164:165]
	ds_read_b128 v[26:29], v25
	ds_read_b128 v[30:33], v25 offset:4096
	ds_read_b128 v[34:37], v25 offset:8192
	ds_read_b128 v[38:41], v25 offset:12288
	ds_read_b128 v[42:45], v25 offset:16384
	ds_read_b128 v[46:49], v25 offset:20480
	ds_read_b128 v[50:53], v25 offset:24576
	ds_read_b128 v[54:57], v25 offset:28672
	v_add_u32_e32 v25, 16, v25
	s_waitcnt vmcnt(60)
	s_waitcnt lgkmcnt(0)
	v_fmac_f32_e32 v18, v114, v26
	v_fmac_f32_e32 v19, v114, v30
	v_fmac_f32_e32 v16, v114, v34
	v_fmac_f32_e32 v17, v114, v38
	v_fmac_f32_e32 v14, v114, v42
	v_fmac_f32_e32 v15, v114, v46
	v_fmac_f32_e32 v12, v114, v50
	v_fmac_f32_e32 v13, v114, v54
	v_fmac_f32_e32 v18, v115, v27
	v_fmac_f32_e32 v19, v115, v31
	v_fmac_f32_e32 v16, v115, v35
	v_fmac_f32_e32 v17, v115, v39
	v_fmac_f32_e32 v14, v115, v43
	v_fmac_f32_e32 v15, v115, v47
	v_fmac_f32_e32 v12, v115, v51
	v_fmac_f32_e32 v13, v115, v55
	v_fmac_f32_e32 v18, v116, v28
	v_fmac_f32_e32 v19, v116, v32
	v_fmac_f32_e32 v16, v116, v36
	v_fmac_f32_e32 v17, v116, v40
	v_fmac_f32_e32 v14, v116, v44
	v_fmac_f32_e32 v15, v116, v48
	v_fmac_f32_e32 v12, v116, v52
	v_fmac_f32_e32 v13, v116, v56
	v_fmac_f32_e32 v18, v117, v29
	v_fmac_f32_e32 v19, v117, v33
	v_fmac_f32_e32 v16, v117, v37
	v_fmac_f32_e32 v17, v117, v41
	v_fmac_f32_e32 v14, v117, v45
	v_fmac_f32_e32 v15, v117, v49
	v_fmac_f32_e32 v12, v117, v53
	v_fmac_f32_e32 v13, v117, v57
	global_load_dword v114, v[166:167], off
	v_lshl_add_u64 v[168:169], v[166:167], 0, v[158:159]
	v_lshl_add_u64 v[170:171], v[166:167], 0, v[160:161]
	v_lshl_add_u64 v[172:173], v[166:167], 0, v[162:163]
	global_load_dword v115, v[168:169], off
	global_load_dword v116, v[170:171], off
	global_load_dword v117, v[172:173], off
	v_lshl_add_u64 v[166:167], v[166:167], 0, v[164:165]
	ds_read_b128 v[26:29], v25
	ds_read_b128 v[30:33], v25 offset:4096
	ds_read_b128 v[34:37], v25 offset:8192
	ds_read_b128 v[38:41], v25 offset:12288
	ds_read_b128 v[42:45], v25 offset:16384
	ds_read_b128 v[46:49], v25 offset:20480
	ds_read_b128 v[50:53], v25 offset:24576
	ds_read_b128 v[54:57], v25 offset:28672
	v_add_u32_e32 v25, 16, v25
	s_waitcnt vmcnt(60)
	s_waitcnt lgkmcnt(0)
	v_fmac_f32_e32 v18, v118, v26
	v_fmac_f32_e32 v19, v118, v30
	v_fmac_f32_e32 v16, v118, v34
	v_fmac_f32_e32 v17, v118, v38
	v_fmac_f32_e32 v14, v118, v42
	v_fmac_f32_e32 v15, v118, v46
	v_fmac_f32_e32 v12, v118, v50
	v_fmac_f32_e32 v13, v118, v54
	v_fmac_f32_e32 v18, v119, v27
	v_fmac_f32_e32 v19, v119, v31
	v_fmac_f32_e32 v16, v119, v35
	v_fmac_f32_e32 v17, v119, v39
	v_fmac_f32_e32 v14, v119, v43
	v_fmac_f32_e32 v15, v119, v47
	v_fmac_f32_e32 v12, v119, v51
	v_fmac_f32_e32 v13, v119, v55
	v_fmac_f32_e32 v18, v120, v28
	v_fmac_f32_e32 v19, v120, v32
	v_fmac_f32_e32 v16, v120, v36
	v_fmac_f32_e32 v17, v120, v40
	v_fmac_f32_e32 v14, v120, v44
	v_fmac_f32_e32 v15, v120, v48
	v_fmac_f32_e32 v12, v120, v52
	v_fmac_f32_e32 v13, v120, v56
	v_fmac_f32_e32 v18, v121, v29
	v_fmac_f32_e32 v19, v121, v33
	v_fmac_f32_e32 v16, v121, v37
	v_fmac_f32_e32 v17, v121, v41
	v_fmac_f32_e32 v14, v121, v45
	v_fmac_f32_e32 v15, v121, v49
	v_fmac_f32_e32 v12, v121, v53
	v_fmac_f32_e32 v13, v121, v57
	global_load_dword v118, v[166:167], off
	v_lshl_add_u64 v[168:169], v[166:167], 0, v[158:159]
	v_lshl_add_u64 v[170:171], v[166:167], 0, v[160:161]
	v_lshl_add_u64 v[172:173], v[166:167], 0, v[162:163]
	global_load_dword v119, v[168:169], off
	global_load_dword v120, v[170:171], off
	global_load_dword v121, v[172:173], off
	v_lshl_add_u64 v[166:167], v[166:167], 0, v[164:165]
	ds_read_b128 v[26:29], v25
	ds_read_b128 v[30:33], v25 offset:4096
	ds_read_b128 v[34:37], v25 offset:8192
	ds_read_b128 v[38:41], v25 offset:12288
	ds_read_b128 v[42:45], v25 offset:16384
	ds_read_b128 v[46:49], v25 offset:20480
	ds_read_b128 v[50:53], v25 offset:24576
	ds_read_b128 v[54:57], v25 offset:28672
	v_add_u32_e32 v25, 16, v25
	s_waitcnt vmcnt(60)
	s_waitcnt lgkmcnt(0)
	v_fmac_f32_e32 v18, v122, v26
	v_fmac_f32_e32 v19, v122, v30
	v_fmac_f32_e32 v16, v122, v34
	v_fmac_f32_e32 v17, v122, v38
	v_fmac_f32_e32 v14, v122, v42
	v_fmac_f32_e32 v15, v122, v46
	v_fmac_f32_e32 v12, v122, v50
	v_fmac_f32_e32 v13, v122, v54
	v_fmac_f32_e32 v18, v123, v27
	v_fmac_f32_e32 v19, v123, v31
	v_fmac_f32_e32 v16, v123, v35
	v_fmac_f32_e32 v17, v123, v39
	v_fmac_f32_e32 v14, v123, v43
	v_fmac_f32_e32 v15, v123, v47
	v_fmac_f32_e32 v12, v123, v51
	v_fmac_f32_e32 v13, v123, v55
	v_fmac_f32_e32 v18, v124, v28
	v_fmac_f32_e32 v19, v124, v32
	v_fmac_f32_e32 v16, v124, v36
	v_fmac_f32_e32 v17, v124, v40
	v_fmac_f32_e32 v14, v124, v44
	v_fmac_f32_e32 v15, v124, v48
	v_fmac_f32_e32 v12, v124, v52
	v_fmac_f32_e32 v13, v124, v56
	v_fmac_f32_e32 v18, v125, v29
	v_fmac_f32_e32 v19, v125, v33
	v_fmac_f32_e32 v16, v125, v37
	v_fmac_f32_e32 v17, v125, v41
	v_fmac_f32_e32 v14, v125, v45
	v_fmac_f32_e32 v15, v125, v49
	v_fmac_f32_e32 v12, v125, v53
	v_fmac_f32_e32 v13, v125, v57
	global_load_dword v122, v[166:167], off
	v_lshl_add_u64 v[168:169], v[166:167], 0, v[158:159]
	v_lshl_add_u64 v[170:171], v[166:167], 0, v[160:161]
	v_lshl_add_u64 v[172:173], v[166:167], 0, v[162:163]
	global_load_dword v123, v[168:169], off
	global_load_dword v124, v[170:171], off
	global_load_dword v125, v[172:173], off
	v_lshl_add_u64 v[166:167], v[166:167], 0, v[164:165]
	ds_read_b128 v[26:29], v25
	ds_read_b128 v[30:33], v25 offset:4096
	ds_read_b128 v[34:37], v25 offset:8192
	ds_read_b128 v[38:41], v25 offset:12288
	ds_read_b128 v[42:45], v25 offset:16384
	ds_read_b128 v[46:49], v25 offset:20480
	ds_read_b128 v[50:53], v25 offset:24576
	ds_read_b128 v[54:57], v25 offset:28672
	v_add_u32_e32 v25, 16, v25
	s_waitcnt vmcnt(60)
	s_waitcnt lgkmcnt(0)
	v_fmac_f32_e32 v18, v126, v26
	v_fmac_f32_e32 v19, v126, v30
	v_fmac_f32_e32 v16, v126, v34
	v_fmac_f32_e32 v17, v126, v38
	v_fmac_f32_e32 v14, v126, v42
	v_fmac_f32_e32 v15, v126, v46
	v_fmac_f32_e32 v12, v126, v50
	v_fmac_f32_e32 v13, v126, v54
	v_fmac_f32_e32 v18, v127, v27
	v_fmac_f32_e32 v19, v127, v31
	v_fmac_f32_e32 v16, v127, v35
	v_fmac_f32_e32 v17, v127, v39
	v_fmac_f32_e32 v14, v127, v43
	v_fmac_f32_e32 v15, v127, v47
	v_fmac_f32_e32 v12, v127, v51
	v_fmac_f32_e32 v13, v127, v55
	v_fmac_f32_e32 v18, v128, v28
	v_fmac_f32_e32 v19, v128, v32
	v_fmac_f32_e32 v16, v128, v36
	v_fmac_f32_e32 v17, v128, v40
	v_fmac_f32_e32 v14, v128, v44
	v_fmac_f32_e32 v15, v128, v48
	v_fmac_f32_e32 v12, v128, v52
	v_fmac_f32_e32 v13, v128, v56
	v_fmac_f32_e32 v18, v129, v29
	v_fmac_f32_e32 v19, v129, v33
	v_fmac_f32_e32 v16, v129, v37
	v_fmac_f32_e32 v17, v129, v41
	v_fmac_f32_e32 v14, v129, v45
	v_fmac_f32_e32 v15, v129, v49
	v_fmac_f32_e32 v12, v129, v53
	v_fmac_f32_e32 v13, v129, v57
	global_load_dword v126, v[166:167], off
	v_lshl_add_u64 v[168:169], v[166:167], 0, v[158:159]
	v_lshl_add_u64 v[170:171], v[166:167], 0, v[160:161]
	v_lshl_add_u64 v[172:173], v[166:167], 0, v[162:163]
	global_load_dword v127, v[168:169], off
	global_load_dword v128, v[170:171], off
	global_load_dword v129, v[172:173], off
	v_lshl_add_u64 v[166:167], v[166:167], 0, v[164:165]
	s_sub_u32 s2, s2, 1
	s_cmp_lg_u32 s2, 0
	s_cbranch_scc1 .Lada_loop
	ds_read_b128 v[26:29], v25
	ds_read_b128 v[30:33], v25 offset:4096
	ds_read_b128 v[34:37], v25 offset:8192
	ds_read_b128 v[38:41], v25 offset:12288
	ds_read_b128 v[42:45], v25 offset:16384
	ds_read_b128 v[46:49], v25 offset:20480
	ds_read_b128 v[50:53], v25 offset:24576
	ds_read_b128 v[54:57], v25 offset:28672
	v_add_u32_e32 v25, 16, v25
	s_waitcnt vmcnt(60)
	s_waitcnt lgkmcnt(0)
	v_fmac_f32_e32 v18, v66, v26
	v_fmac_f32_e32 v19, v66, v30
	v_fmac_f32_e32 v16, v66, v34
	v_fmac_f32_e32 v17, v66, v38
	v_fmac_f32_e32 v14, v66, v42
	v_fmac_f32_e32 v15, v66, v46
	v_fmac_f32_e32 v12, v66, v50
	v_fmac_f32_e32 v13, v66, v54
	v_fmac_f32_e32 v18, v67, v27
	v_fmac_f32_e32 v19, v67, v31
	v_fmac_f32_e32 v16, v67, v35
	v_fmac_f32_e32 v17, v67, v39
	v_fmac_f32_e32 v14, v67, v43
	v_fmac_f32_e32 v15, v67, v47
	v_fmac_f32_e32 v12, v67, v51
	v_fmac_f32_e32 v13, v67, v55
	v_fmac_f32_e32 v18, v68, v28
	v_fmac_f32_e32 v19, v68, v32
	v_fmac_f32_e32 v16, v68, v36
	v_fmac_f32_e32 v17, v68, v40
	v_fmac_f32_e32 v14, v68, v44
	v_fmac_f32_e32 v15, v68, v48
	v_fmac_f32_e32 v12, v68, v52
	v_fmac_f32_e32 v13, v68, v56
	v_fmac_f32_e32 v18, v69, v29
	v_fmac_f32_e32 v19, v69, v33
	v_fmac_f32_e32 v16, v69, v37
	v_fmac_f32_e32 v17, v69, v41
	v_fmac_f32_e32 v14, v69, v45
	v_fmac_f32_e32 v15, v69, v49
	v_fmac_f32_e32 v12, v69, v53
	v_fmac_f32_e32 v13, v69, v57
	ds_read_b128 v[26:29], v25
	ds_read_b128 v[30:33], v25 offset:4096
	ds_read_b128 v[34:37], v25 offset:8192
	ds_read_b128 v[38:41], v25 offset:12288
	ds_read_b128 v[42:45], v25 offset:16384
	ds_read_b128 v[46:49], v25 offset:20480
	ds_read_b128 v[50:53], v25 offset:24576
	ds_read_b128 v[54:57], v25 offset:28672
	v_add_u32_e32 v25, 16, v25
	s_waitcnt vmcnt(56)
	s_waitcnt lgkmcnt(0)
	v_fmac_f32_e32 v18, v70, v26
	v_fmac_f32_e32 v19, v70, v30
	v_fmac_f32_e32 v16, v70, v34
	v_fmac_f32_e32 v17, v70, v38
	v_fmac_f32_e32 v14, v70, v42
	v_fmac_f32_e32 v15, v70, v46
	v_fmac_f32_e32 v12, v70, v50
	v_fmac_f32_e32 v13, v70, v54
	v_fmac_f32_e32 v18, v71, v27
	v_fmac_f32_e32 v19, v71, v31
	v_fmac_f32_e32 v16, v71, v35
	v_fmac_f32_e32 v17, v71, v39
	v_fmac_f32_e32 v14, v71, v43
	v_fmac_f32_e32 v15, v71, v47
	v_fmac_f32_e32 v12, v71, v51
	v_fmac_f32_e32 v13, v71, v55
	v_fmac_f32_e32 v18, v72, v28
	v_fmac_f32_e32 v19, v72, v32
	v_fmac_f32_e32 v16, v72, v36
	v_fmac_f32_e32 v17, v72, v40
	v_fmac_f32_e32 v14, v72, v44
	v_fmac_f32_e32 v15, v72, v48
	v_fmac_f32_e32 v12, v72, v52
	v_fmac_f32_e32 v13, v72, v56
	v_fmac_f32_e32 v18, v73, v29
	v_fmac_f32_e32 v19, v73, v33
	v_fmac_f32_e32 v16, v73, v37
	v_fmac_f32_e32 v17, v73, v41
	v_fmac_f32_e32 v14, v73, v45
	v_fmac_f32_e32 v15, v73, v49
	v_fmac_f32_e32 v12, v73, v53
	v_fmac_f32_e32 v13, v73, v57
	ds_read_b128 v[26:29], v25
	ds_read_b128 v[30:33], v25 offset:4096
	ds_read_b128 v[34:37], v25 offset:8192
	ds_read_b128 v[38:41], v25 offset:12288
	ds_read_b128 v[42:45], v25 offset:16384
	ds_read_b128 v[46:49], v25 offset:20480
	ds_read_b128 v[50:53], v25 offset:24576
	ds_read_b128 v[54:57], v25 offset:28672
	v_add_u32_e32 v25, 16, v25
	s_waitcnt vmcnt(52)
	s_waitcnt lgkmcnt(0)
	v_fmac_f32_e32 v18, v74, v26
	v_fmac_f32_e32 v19, v74, v30
	v_fmac_f32_e32 v16, v74, v34
	v_fmac_f32_e32 v17, v74, v38
	v_fmac_f32_e32 v14, v74, v42
	v_fmac_f32_e32 v15, v74, v46
	v_fmac_f32_e32 v12, v74, v50
	v_fmac_f32_e32 v13, v74, v54
	v_fmac_f32_e32 v18, v75, v27
	v_fmac_f32_e32 v19, v75, v31
	v_fmac_f32_e32 v16, v75, v35
	v_fmac_f32_e32 v17, v75, v39
	v_fmac_f32_e32 v14, v75, v43
	v_fmac_f32_e32 v15, v75, v47
	v_fmac_f32_e32 v12, v75, v51
	v_fmac_f32_e32 v13, v75, v55
	v_fmac_f32_e32 v18, v76, v28
	v_fmac_f32_e32 v19, v76, v32
	v_fmac_f32_e32 v16, v76, v36
	v_fmac_f32_e32 v17, v76, v40
	v_fmac_f32_e32 v14, v76, v44
	v_fmac_f32_e32 v15, v76, v48
	v_fmac_f32_e32 v12, v76, v52
	v_fmac_f32_e32 v13, v76, v56
	v_fmac_f32_e32 v18, v77, v29
	v_fmac_f32_e32 v19, v77, v33
	v_fmac_f32_e32 v16, v77, v37
	v_fmac_f32_e32 v17, v77, v41
	v_fmac_f32_e32 v14, v77, v45
	v_fmac_f32_e32 v15, v77, v49
	v_fmac_f32_e32 v12, v77, v53
	v_fmac_f32_e32 v13, v77, v57
	ds_read_b128 v[26:29], v25
	ds_read_b128 v[30:33], v25 offset:4096
	ds_read_b128 v[34:37], v25 offset:8192
	ds_read_b128 v[38:41], v25 offset:12288
	ds_read_b128 v[42:45], v25 offset:16384
	ds_read_b128 v[46:49], v25 offset:20480
	ds_read_b128 v[50:53], v25 offset:24576
	ds_read_b128 v[54:57], v25 offset:28672
	v_add_u32_e32 v25, 16, v25
	s_waitcnt vmcnt(48)
	s_waitcnt lgkmcnt(0)
	v_fmac_f32_e32 v18, v78, v26
	v_fmac_f32_e32 v19, v78, v30
	v_fmac_f32_e32 v16, v78, v34
	v_fmac_f32_e32 v17, v78, v38
	v_fmac_f32_e32 v14, v78, v42
	v_fmac_f32_e32 v15, v78, v46
	v_fmac_f32_e32 v12, v78, v50
	v_fmac_f32_e32 v13, v78, v54
	v_fmac_f32_e32 v18, v79, v27
	v_fmac_f32_e32 v19, v79, v31
	v_fmac_f32_e32 v16, v79, v35
	v_fmac_f32_e32 v17, v79, v39
	v_fmac_f32_e32 v14, v79, v43
	v_fmac_f32_e32 v15, v79, v47
	v_fmac_f32_e32 v12, v79, v51
	v_fmac_f32_e32 v13, v79, v55
	v_fmac_f32_e32 v18, v80, v28
	v_fmac_f32_e32 v19, v80, v32
	v_fmac_f32_e32 v16, v80, v36
	v_fmac_f32_e32 v17, v80, v40
	v_fmac_f32_e32 v14, v80, v44
	v_fmac_f32_e32 v15, v80, v48
	v_fmac_f32_e32 v12, v80, v52
	v_fmac_f32_e32 v13, v80, v56
	v_fmac_f32_e32 v18, v81, v29
	v_fmac_f32_e32 v19, v81, v33
	v_fmac_f32_e32 v16, v81, v37
	v_fmac_f32_e32 v17, v81, v41
	v_fmac_f32_e32 v14, v81, v45
	v_fmac_f32_e32 v15, v81, v49
	v_fmac_f32_e32 v12, v81, v53
	v_fmac_f32_e32 v13, v81, v57
	ds_read_b128 v[26:29], v25
	ds_read_b128 v[30:33], v25 offset:4096
	ds_read_b128 v[34:37], v25 offset:8192
	ds_read_b128 v[38:41], v25 offset:12288
	ds_read_b128 v[42:45], v25 offset:16384
	ds_read_b128 v[46:49], v25 offset:20480
	ds_read_b128 v[50:53], v25 offset:24576
	ds_read_b128 v[54:57], v25 offset:28672
	v_add_u32_e32 v25, 16, v25
	s_waitcnt vmcnt(44)
	s_waitcnt lgkmcnt(0)
	v_fmac_f32_e32 v18, v82, v26
	v_fmac_f32_e32 v19, v82, v30
	v_fmac_f32_e32 v16, v82, v34
	v_fmac_f32_e32 v17, v82, v38
	v_fmac_f32_e32 v14, v82, v42
	v_fmac_f32_e32 v15, v82, v46
	v_fmac_f32_e32 v12, v82, v50
	v_fmac_f32_e32 v13, v82, v54
	v_fmac_f32_e32 v18, v83, v27
	v_fmac_f32_e32 v19, v83, v31
	v_fmac_f32_e32 v16, v83, v35
	v_fmac_f32_e32 v17, v83, v39
	v_fmac_f32_e32 v14, v83, v43
	v_fmac_f32_e32 v15, v83, v47
	v_fmac_f32_e32 v12, v83, v51
	v_fmac_f32_e32 v13, v83, v55
	v_fmac_f32_e32 v18, v84, v28
	v_fmac_f32_e32 v19, v84, v32
	v_fmac_f32_e32 v16, v84, v36
	v_fmac_f32_e32 v17, v84, v40
	v_fmac_f32_e32 v14, v84, v44
	v_fmac_f32_e32 v15, v84, v48
	v_fmac_f32_e32 v12, v84, v52
	v_fmac_f32_e32 v13, v84, v56
	v_fmac_f32_e32 v18, v85, v29
	v_fmac_f32_e32 v19, v85, v33
	v_fmac_f32_e32 v16, v85, v37
	v_fmac_f32_e32 v17, v85, v41
	v_fmac_f32_e32 v14, v85, v45
	v_fmac_f32_e32 v15, v85, v49
	v_fmac_f32_e32 v12, v85, v53
	v_fmac_f32_e32 v13, v85, v57
	ds_read_b128 v[26:29], v25
	ds_read_b128 v[30:33], v25 offset:4096
	ds_read_b128 v[34:37], v25 offset:8192
	ds_read_b128 v[38:41], v25 offset:12288
	ds_read_b128 v[42:45], v25 offset:16384
	ds_read_b128 v[46:49], v25 offset:20480
	ds_read_b128 v[50:53], v25 offset:24576
	ds_read_b128 v[54:57], v25 offset:28672
	v_add_u32_e32 v25, 16, v25
	s_waitcnt vmcnt(40)
	s_waitcnt lgkmcnt(0)
	v_fmac_f32_e32 v18, v86, v26
	v_fmac_f32_e32 v19, v86, v30
	v_fmac_f32_e32 v16, v86, v34
	v_fmac_f32_e32 v17, v86, v38
	v_fmac_f32_e32 v14, v86, v42
	v_fmac_f32_e32 v15, v86, v46
	v_fmac_f32_e32 v12, v86, v50
	v_fmac_f32_e32 v13, v86, v54
	v_fmac_f32_e32 v18, v87, v27
	v_fmac_f32_e32 v19, v87, v31
	v_fmac_f32_e32 v16, v87, v35
	v_fmac_f32_e32 v17, v87, v39
	v_fmac_f32_e32 v14, v87, v43
	v_fmac_f32_e32 v15, v87, v47
	v_fmac_f32_e32 v12, v87, v51
	v_fmac_f32_e32 v13, v87, v55
	v_fmac_f32_e32 v18, v88, v28
	v_fmac_f32_e32 v19, v88, v32
	v_fmac_f32_e32 v16, v88, v36
	v_fmac_f32_e32 v17, v88, v40
	v_fmac_f32_e32 v14, v88, v44
	v_fmac_f32_e32 v15, v88, v48
	v_fmac_f32_e32 v12, v88, v52
	v_fmac_f32_e32 v13, v88, v56
	v_fmac_f32_e32 v18, v89, v29
	v_fmac_f32_e32 v19, v89, v33
	v_fmac_f32_e32 v16, v89, v37
	v_fmac_f32_e32 v17, v89, v41
	v_fmac_f32_e32 v14, v89, v45
	v_fmac_f32_e32 v15, v89, v49
	v_fmac_f32_e32 v12, v89, v53
	v_fmac_f32_e32 v13, v89, v57
	ds_read_b128 v[26:29], v25
	ds_read_b128 v[30:33], v25 offset:4096
	ds_read_b128 v[34:37], v25 offset:8192
	ds_read_b128 v[38:41], v25 offset:12288
	ds_read_b128 v[42:45], v25 offset:16384
	ds_read_b128 v[46:49], v25 offset:20480
	ds_read_b128 v[50:53], v25 offset:24576
	ds_read_b128 v[54:57], v25 offset:28672
	v_add_u32_e32 v25, 16, v25
	s_waitcnt vmcnt(36)
	s_waitcnt lgkmcnt(0)
	v_fmac_f32_e32 v18, v90, v26
	v_fmac_f32_e32 v19, v90, v30
	v_fmac_f32_e32 v16, v90, v34
	v_fmac_f32_e32 v17, v90, v38
	v_fmac_f32_e32 v14, v90, v42
	v_fmac_f32_e32 v15, v90, v46
	v_fmac_f32_e32 v12, v90, v50
	v_fmac_f32_e32 v13, v90, v54
	v_fmac_f32_e32 v18, v91, v27
	v_fmac_f32_e32 v19, v91, v31
	v_fmac_f32_e32 v16, v91, v35
	v_fmac_f32_e32 v17, v91, v39
	v_fmac_f32_e32 v14, v91, v43
	v_fmac_f32_e32 v15, v91, v47
	v_fmac_f32_e32 v12, v91, v51
	v_fmac_f32_e32 v13, v91, v55
	v_fmac_f32_e32 v18, v92, v28
	v_fmac_f32_e32 v19, v92, v32
	v_fmac_f32_e32 v16, v92, v36
	v_fmac_f32_e32 v17, v92, v40
	v_fmac_f32_e32 v14, v92, v44
	v_fmac_f32_e32 v15, v92, v48
	v_fmac_f32_e32 v12, v92, v52
	v_fmac_f32_e32 v13, v92, v56
	v_fmac_f32_e32 v18, v93, v29
	v_fmac_f32_e32 v19, v93, v33
	v_fmac_f32_e32 v16, v93, v37
	v_fmac_f32_e32 v17, v93, v41
	v_fmac_f32_e32 v14, v93, v45
	v_fmac_f32_e32 v15, v93, v49
	v_fmac_f32_e32 v12, v93, v53
	v_fmac_f32_e32 v13, v93, v57
	ds_read_b128 v[26:29], v25
	ds_read_b128 v[30:33], v25 offset:4096
	ds_read_b128 v[34:37], v25 offset:8192
	ds_read_b128 v[38:41], v25 offset:12288
	ds_read_b128 v[42:45], v25 offset:16384
	ds_read_b128 v[46:49], v25 offset:20480
	ds_read_b128 v[50:53], v25 offset:24576
	ds_read_b128 v[54:57], v25 offset:28672
	v_add_u32_e32 v25, 16, v25
	s_waitcnt vmcnt(32)
	s_waitcnt lgkmcnt(0)
	v_fmac_f32_e32 v18, v94, v26
	v_fmac_f32_e32 v19, v94, v30
	v_fmac_f32_e32 v16, v94, v34
	v_fmac_f32_e32 v17, v94, v38
	v_fmac_f32_e32 v14, v94, v42
	v_fmac_f32_e32 v15, v94, v46
	v_fmac_f32_e32 v12, v94, v50
	v_fmac_f32_e32 v13, v94, v54
	v_fmac_f32_e32 v18, v95, v27
	v_fmac_f32_e32 v19, v95, v31
	v_fmac_f32_e32 v16, v95, v35
	v_fmac_f32_e32 v17, v95, v39
	v_fmac_f32_e32 v14, v95, v43
	v_fmac_f32_e32 v15, v95, v47
	v_fmac_f32_e32 v12, v95, v51
	v_fmac_f32_e32 v13, v95, v55
	v_fmac_f32_e32 v18, v96, v28
	v_fmac_f32_e32 v19, v96, v32
	v_fmac_f32_e32 v16, v96, v36
	v_fmac_f32_e32 v17, v96, v40
	v_fmac_f32_e32 v14, v96, v44
	v_fmac_f32_e32 v15, v96, v48
	v_fmac_f32_e32 v12, v96, v52
	v_fmac_f32_e32 v13, v96, v56
	v_fmac_f32_e32 v18, v97, v29
	v_fmac_f32_e32 v19, v97, v33
	v_fmac_f32_e32 v16, v97, v37
	v_fmac_f32_e32 v17, v97, v41
	v_fmac_f32_e32 v14, v97, v45
	v_fmac_f32_e32 v15, v97, v49
	v_fmac_f32_e32 v12, v97, v53
	v_fmac_f32_e32 v13, v97, v57
	ds_read_b128 v[26:29], v25
	ds_read_b128 v[30:33], v25 offset:4096
	ds_read_b128 v[34:37], v25 offset:8192
	ds_read_b128 v[38:41], v25 offset:12288
	ds_read_b128 v[42:45], v25 offset:16384
	ds_read_b128 v[46:49], v25 offset:20480
	ds_read_b128 v[50:53], v25 offset:24576
	ds_read_b128 v[54:57], v25 offset:28672
	v_add_u32_e32 v25, 16, v25
	s_waitcnt vmcnt(28)
	s_waitcnt lgkmcnt(0)
	v_fmac_f32_e32 v18, v98, v26
	v_fmac_f32_e32 v19, v98, v30
	v_fmac_f32_e32 v16, v98, v34
	v_fmac_f32_e32 v17, v98, v38
	v_fmac_f32_e32 v14, v98, v42
	v_fmac_f32_e32 v15, v98, v46
	v_fmac_f32_e32 v12, v98, v50
	v_fmac_f32_e32 v13, v98, v54
	v_fmac_f32_e32 v18, v99, v27
	v_fmac_f32_e32 v19, v99, v31
	v_fmac_f32_e32 v16, v99, v35
	v_fmac_f32_e32 v17, v99, v39
	v_fmac_f32_e32 v14, v99, v43
	v_fmac_f32_e32 v15, v99, v47
	v_fmac_f32_e32 v12, v99, v51
	v_fmac_f32_e32 v13, v99, v55
	v_fmac_f32_e32 v18, v100, v28
	v_fmac_f32_e32 v19, v100, v32
	v_fmac_f32_e32 v16, v100, v36
	v_fmac_f32_e32 v17, v100, v40
	v_fmac_f32_e32 v14, v100, v44
	v_fmac_f32_e32 v15, v100, v48
	v_fmac_f32_e32 v12, v100, v52
	v_fmac_f32_e32 v13, v100, v56
	v_fmac_f32_e32 v18, v101, v29
	v_fmac_f32_e32 v19, v101, v33
	v_fmac_f32_e32 v16, v101, v37
	v_fmac_f32_e32 v17, v101, v41
	v_fmac_f32_e32 v14, v101, v45
	v_fmac_f32_e32 v15, v101, v49
	v_fmac_f32_e32 v12, v101, v53
	v_fmac_f32_e32 v13, v101, v57
	ds_read_b128 v[26:29], v25
	ds_read_b128 v[30:33], v25 offset:4096
	ds_read_b128 v[34:37], v25 offset:8192
	ds_read_b128 v[38:41], v25 offset:12288
	ds_read_b128 v[42:45], v25 offset:16384
	ds_read_b128 v[46:49], v25 offset:20480
	ds_read_b128 v[50:53], v25 offset:24576
	ds_read_b128 v[54:57], v25 offset:28672
	v_add_u32_e32 v25, 16, v25
	s_waitcnt vmcnt(24)
	s_waitcnt lgkmcnt(0)
	v_fmac_f32_e32 v18, v102, v26
	v_fmac_f32_e32 v19, v102, v30
	v_fmac_f32_e32 v16, v102, v34
	v_fmac_f32_e32 v17, v102, v38
	v_fmac_f32_e32 v14, v102, v42
	v_fmac_f32_e32 v15, v102, v46
	v_fmac_f32_e32 v12, v102, v50
	v_fmac_f32_e32 v13, v102, v54
	v_fmac_f32_e32 v18, v103, v27
	v_fmac_f32_e32 v19, v103, v31
	v_fmac_f32_e32 v16, v103, v35
	v_fmac_f32_e32 v17, v103, v39
	v_fmac_f32_e32 v14, v103, v43
	v_fmac_f32_e32 v15, v103, v47
	v_fmac_f32_e32 v12, v103, v51
	v_fmac_f32_e32 v13, v103, v55
	v_fmac_f32_e32 v18, v104, v28
	v_fmac_f32_e32 v19, v104, v32
	v_fmac_f32_e32 v16, v104, v36
	v_fmac_f32_e32 v17, v104, v40
	v_fmac_f32_e32 v14, v104, v44
	v_fmac_f32_e32 v15, v104, v48
	v_fmac_f32_e32 v12, v104, v52
	v_fmac_f32_e32 v13, v104, v56
	v_fmac_f32_e32 v18, v105, v29
	v_fmac_f32_e32 v19, v105, v33
	v_fmac_f32_e32 v16, v105, v37
	v_fmac_f32_e32 v17, v105, v41
	v_fmac_f32_e32 v14, v105, v45
	v_fmac_f32_e32 v15, v105, v49
	v_fmac_f32_e32 v12, v105, v53
	v_fmac_f32_e32 v13, v105, v57
	ds_read_b128 v[26:29], v25
	ds_read_b128 v[30:33], v25 offset:4096
	ds_read_b128 v[34:37], v25 offset:8192
	ds_read_b128 v[38:41], v25 offset:12288
	ds_read_b128 v[42:45], v25 offset:16384
	ds_read_b128 v[46:49], v25 offset:20480
	ds_read_b128 v[50:53], v25 offset:24576
	ds_read_b128 v[54:57], v25 offset:28672
	v_add_u32_e32 v25, 16, v25
	s_waitcnt vmcnt(20)
	s_waitcnt lgkmcnt(0)
	v_fmac_f32_e32 v18, v106, v26
	v_fmac_f32_e32 v19, v106, v30
	v_fmac_f32_e32 v16, v106, v34
	v_fmac_f32_e32 v17, v106, v38
	v_fmac_f32_e32 v14, v106, v42
	v_fmac_f32_e32 v15, v106, v46
	v_fmac_f32_e32 v12, v106, v50
	v_fmac_f32_e32 v13, v106, v54
	v_fmac_f32_e32 v18, v107, v27
	v_fmac_f32_e32 v19, v107, v31
	v_fmac_f32_e32 v16, v107, v35
	v_fmac_f32_e32 v17, v107, v39
	v_fmac_f32_e32 v14, v107, v43
	v_fmac_f32_e32 v15, v107, v47
	v_fmac_f32_e32 v12, v107, v51
	v_fmac_f32_e32 v13, v107, v55
	v_fmac_f32_e32 v18, v108, v28
	v_fmac_f32_e32 v19, v108, v32
	v_fmac_f32_e32 v16, v108, v36
	v_fmac_f32_e32 v17, v108, v40
	v_fmac_f32_e32 v14, v108, v44
	v_fmac_f32_e32 v15, v108, v48
	v_fmac_f32_e32 v12, v108, v52
	v_fmac_f32_e32 v13, v108, v56
	v_fmac_f32_e32 v18, v109, v29
	v_fmac_f32_e32 v19, v109, v33
	v_fmac_f32_e32 v16, v109, v37
	v_fmac_f32_e32 v17, v109, v41
	v_fmac_f32_e32 v14, v109, v45
	v_fmac_f32_e32 v15, v109, v49
	v_fmac_f32_e32 v12, v109, v53
	v_fmac_f32_e32 v13, v109, v57
	ds_read_b128 v[26:29], v25
	ds_read_b128 v[30:33], v25 offset:4096
	ds_read_b128 v[34:37], v25 offset:8192
	ds_read_b128 v[38:41], v25 offset:12288
	ds_read_b128 v[42:45], v25 offset:16384
	ds_read_b128 v[46:49], v25 offset:20480
	ds_read_b128 v[50:53], v25 offset:24576
	ds_read_b128 v[54:57], v25 offset:28672
	v_add_u32_e32 v25, 16, v25
	s_waitcnt vmcnt(16)
	s_waitcnt lgkmcnt(0)
	v_fmac_f32_e32 v18, v110, v26
	v_fmac_f32_e32 v19, v110, v30
	v_fmac_f32_e32 v16, v110, v34
	v_fmac_f32_e32 v17, v110, v38
	v_fmac_f32_e32 v14, v110, v42
	v_fmac_f32_e32 v15, v110, v46
	v_fmac_f32_e32 v12, v110, v50
	v_fmac_f32_e32 v13, v110, v54
	v_fmac_f32_e32 v18, v111, v27
	v_fmac_f32_e32 v19, v111, v31
	v_fmac_f32_e32 v16, v111, v35
	v_fmac_f32_e32 v17, v111, v39
	v_fmac_f32_e32 v14, v111, v43
	v_fmac_f32_e32 v15, v111, v47
	v_fmac_f32_e32 v12, v111, v51
	v_fmac_f32_e32 v13, v111, v55
	v_fmac_f32_e32 v18, v112, v28
	v_fmac_f32_e32 v19, v112, v32
	v_fmac_f32_e32 v16, v112, v36
	v_fmac_f32_e32 v17, v112, v40
	v_fmac_f32_e32 v14, v112, v44
	v_fmac_f32_e32 v15, v112, v48
	v_fmac_f32_e32 v12, v112, v52
	v_fmac_f32_e32 v13, v112, v56
	v_fmac_f32_e32 v18, v113, v29
	v_fmac_f32_e32 v19, v113, v33
	v_fmac_f32_e32 v16, v113, v37
	v_fmac_f32_e32 v17, v113, v41
	v_fmac_f32_e32 v14, v113, v45
	v_fmac_f32_e32 v15, v113, v49
	v_fmac_f32_e32 v12, v113, v53
	v_fmac_f32_e32 v13, v113, v57
	ds_read_b128 v[26:29], v25
	ds_read_b128 v[30:33], v25 offset:4096
	ds_read_b128 v[34:37], v25 offset:8192
	ds_read_b128 v[38:41], v25 offset:12288
	ds_read_b128 v[42:45], v25 offset:16384
	ds_read_b128 v[46:49], v25 offset:20480
	ds_read_b128 v[50:53], v25 offset:24576
	ds_read_b128 v[54:57], v25 offset:28672
	v_add_u32_e32 v25, 16, v25
	s_waitcnt vmcnt(12)
	s_waitcnt lgkmcnt(0)
	v_fmac_f32_e32 v18, v114, v26
	v_fmac_f32_e32 v19, v114, v30
	v_fmac_f32_e32 v16, v114, v34
	v_fmac_f32_e32 v17, v114, v38
	v_fmac_f32_e32 v14, v114, v42
	v_fmac_f32_e32 v15, v114, v46
	v_fmac_f32_e32 v12, v114, v50
	v_fmac_f32_e32 v13, v114, v54
	v_fmac_f32_e32 v18, v115, v27
	v_fmac_f32_e32 v19, v115, v31
	v_fmac_f32_e32 v16, v115, v35
	v_fmac_f32_e32 v17, v115, v39
	v_fmac_f32_e32 v14, v115, v43
	v_fmac_f32_e32 v15, v115, v47
	v_fmac_f32_e32 v12, v115, v51
	v_fmac_f32_e32 v13, v115, v55
	v_fmac_f32_e32 v18, v116, v28
	v_fmac_f32_e32 v19, v116, v32
	v_fmac_f32_e32 v16, v116, v36
	v_fmac_f32_e32 v17, v116, v40
	v_fmac_f32_e32 v14, v116, v44
	v_fmac_f32_e32 v15, v116, v48
	v_fmac_f32_e32 v12, v116, v52
	v_fmac_f32_e32 v13, v116, v56
	v_fmac_f32_e32 v18, v117, v29
	v_fmac_f32_e32 v19, v117, v33
	v_fmac_f32_e32 v16, v117, v37
	v_fmac_f32_e32 v17, v117, v41
	v_fmac_f32_e32 v14, v117, v45
	v_fmac_f32_e32 v15, v117, v49
	v_fmac_f32_e32 v12, v117, v53
	v_fmac_f32_e32 v13, v117, v57
	ds_read_b128 v[26:29], v25
	ds_read_b128 v[30:33], v25 offset:4096
	ds_read_b128 v[34:37], v25 offset:8192
	ds_read_b128 v[38:41], v25 offset:12288
	ds_read_b128 v[42:45], v25 offset:16384
	ds_read_b128 v[46:49], v25 offset:20480
	ds_read_b128 v[50:53], v25 offset:24576
	ds_read_b128 v[54:57], v25 offset:28672
	v_add_u32_e32 v25, 16, v25
	s_waitcnt vmcnt(8)
	s_waitcnt lgkmcnt(0)
	v_fmac_f32_e32 v18, v118, v26
	v_fmac_f32_e32 v19, v118, v30
	v_fmac_f32_e32 v16, v118, v34
	v_fmac_f32_e32 v17, v118, v38
	v_fmac_f32_e32 v14, v118, v42
	v_fmac_f32_e32 v15, v118, v46
	v_fmac_f32_e32 v12, v118, v50
	v_fmac_f32_e32 v13, v118, v54
	v_fmac_f32_e32 v18, v119, v27
	v_fmac_f32_e32 v19, v119, v31
	v_fmac_f32_e32 v16, v119, v35
	v_fmac_f32_e32 v17, v119, v39
	v_fmac_f32_e32 v14, v119, v43
	v_fmac_f32_e32 v15, v119, v47
	v_fmac_f32_e32 v12, v119, v51
	v_fmac_f32_e32 v13, v119, v55
	v_fmac_f32_e32 v18, v120, v28
	v_fmac_f32_e32 v19, v120, v32
	v_fmac_f32_e32 v16, v120, v36
	v_fmac_f32_e32 v17, v120, v40
	v_fmac_f32_e32 v14, v120, v44
	v_fmac_f32_e32 v15, v120, v48
	v_fmac_f32_e32 v12, v120, v52
	v_fmac_f32_e32 v13, v120, v56
	v_fmac_f32_e32 v18, v121, v29
	v_fmac_f32_e32 v19, v121, v33
	v_fmac_f32_e32 v16, v121, v37
	v_fmac_f32_e32 v17, v121, v41
	v_fmac_f32_e32 v14, v121, v45
	v_fmac_f32_e32 v15, v121, v49
	v_fmac_f32_e32 v12, v121, v53
	v_fmac_f32_e32 v13, v121, v57
	ds_read_b128 v[26:29], v25
	ds_read_b128 v[30:33], v25 offset:4096
	ds_read_b128 v[34:37], v25 offset:8192
	ds_read_b128 v[38:41], v25 offset:12288
	ds_read_b128 v[42:45], v25 offset:16384
	ds_read_b128 v[46:49], v25 offset:20480
	ds_read_b128 v[50:53], v25 offset:24576
	ds_read_b128 v[54:57], v25 offset:28672
	v_add_u32_e32 v25, 16, v25
	s_waitcnt vmcnt(4)
	s_waitcnt lgkmcnt(0)
	v_fmac_f32_e32 v18, v122, v26
	v_fmac_f32_e32 v19, v122, v30
	v_fmac_f32_e32 v16, v122, v34
	v_fmac_f32_e32 v17, v122, v38
	v_fmac_f32_e32 v14, v122, v42
	v_fmac_f32_e32 v15, v122, v46
	v_fmac_f32_e32 v12, v122, v50
	v_fmac_f32_e32 v13, v122, v54
	v_fmac_f32_e32 v18, v123, v27
	v_fmac_f32_e32 v19, v123, v31
	v_fmac_f32_e32 v16, v123, v35
	v_fmac_f32_e32 v17, v123, v39
	v_fmac_f32_e32 v14, v123, v43
	v_fmac_f32_e32 v15, v123, v47
	v_fmac_f32_e32 v12, v123, v51
	v_fmac_f32_e32 v13, v123, v55
	v_fmac_f32_e32 v18, v124, v28
	v_fmac_f32_e32 v19, v124, v32
	v_fmac_f32_e32 v16, v124, v36
	v_fmac_f32_e32 v17, v124, v40
	v_fmac_f32_e32 v14, v124, v44
	v_fmac_f32_e32 v15, v124, v48
	v_fmac_f32_e32 v12, v124, v52
	v_fmac_f32_e32 v13, v124, v56
	v_fmac_f32_e32 v18, v125, v29
	v_fmac_f32_e32 v19, v125, v33
	v_fmac_f32_e32 v16, v125, v37
	v_fmac_f32_e32 v17, v125, v41
	v_fmac_f32_e32 v14, v125, v45
	v_fmac_f32_e32 v15, v125, v49
	v_fmac_f32_e32 v12, v125, v53
	v_fmac_f32_e32 v13, v125, v57
	ds_read_b128 v[26:29], v25
	ds_read_b128 v[30:33], v25 offset:4096
	ds_read_b128 v[34:37], v25 offset:8192
	ds_read_b128 v[38:41], v25 offset:12288
	ds_read_b128 v[42:45], v25 offset:16384
	ds_read_b128 v[46:49], v25 offset:20480
	ds_read_b128 v[50:53], v25 offset:24576
	ds_read_b128 v[54:57], v25 offset:28672
	v_add_u32_e32 v25, 16, v25
	s_waitcnt vmcnt(0)
	s_waitcnt lgkmcnt(0)
	v_fmac_f32_e32 v18, v126, v26
	v_fmac_f32_e32 v19, v126, v30
	v_fmac_f32_e32 v16, v126, v34
	v_fmac_f32_e32 v17, v126, v38
	v_fmac_f32_e32 v14, v126, v42
	v_fmac_f32_e32 v15, v126, v46
	v_fmac_f32_e32 v12, v126, v50
	v_fmac_f32_e32 v13, v126, v54
	v_fmac_f32_e32 v18, v127, v27
	v_fmac_f32_e32 v19, v127, v31
	v_fmac_f32_e32 v16, v127, v35
	v_fmac_f32_e32 v17, v127, v39
	v_fmac_f32_e32 v14, v127, v43
	v_fmac_f32_e32 v15, v127, v47
	v_fmac_f32_e32 v12, v127, v51
	v_fmac_f32_e32 v13, v127, v55
	v_fmac_f32_e32 v18, v128, v28
	v_fmac_f32_e32 v19, v128, v32
	v_fmac_f32_e32 v16, v128, v36
	v_fmac_f32_e32 v17, v128, v40
	v_fmac_f32_e32 v14, v128, v44
	v_fmac_f32_e32 v15, v128, v48
	v_fmac_f32_e32 v12, v128, v52
	v_fmac_f32_e32 v13, v128, v56
	v_fmac_f32_e32 v18, v129, v29
	v_fmac_f32_e32 v19, v129, v33
	v_fmac_f32_e32 v16, v129, v37
	v_fmac_f32_e32 v17, v129, v41
	v_fmac_f32_e32 v14, v129, v45
	v_fmac_f32_e32 v15, v129, v49
	v_fmac_f32_e32 v12, v129, v53
	v_fmac_f32_e32 v13, v129, v57
	ds_write2st64_b32 v21, v18, v19 offset0:128 offset1:129
	ds_write2st64_b32 v21, v16, v17 offset0:130 offset1:131
	ds_write2st64_b32 v21, v14, v15 offset0:132 offset1:133
	ds_write2st64_b32 v21, v12, v13 offset0:134 offset1:135
	s_waitcnt lgkmcnt(0)
	s_barrier
	s_and_saveexec_b64 s[2:3], s[40:41]
	s_cbranch_execz .LBB0_533
	s_mul_i32 s5, s4, 0xc00
	v_readlane_b32 s44, v252, 15
	s_lshl_b32 s7, s4, 3
	v_add_u32_e32 v10, s5, v8
	v_readlane_b32 s56, v252, 27
	v_readlane_b32 s57, v252, 28
	v_readlane_b32 s4, v255, 10
	v_ashrrev_i32_e32 v11, 31, v10
	v_readlane_b32 s52, v252, 23
	v_readlane_b32 s53, v252, 24
	v_readlane_b32 s56, v254, 57
	v_readlane_b32 s5, v255, 11
	v_readlane_b32 s57, v254, 58
	v_lshl_add_u64 v[10:11], v[10:11], 2, s[52:53]
	v_lshl_add_u64 v[8:9], v[8:9], 2, s[4:5]
	s_mov_b64 s[4:5], 0
	v_mov_b32_e32 v12, v24
	v_mov_b32_e32 v13, v2
	v_readlane_b32 s45, v252, 16
	v_readlane_b32 s46, v252, 17
	v_readlane_b32 s47, v252, 18
	v_readlane_b32 s48, v252, 19
	v_readlane_b32 s49, v252, 20
	v_readlane_b32 s50, v252, 21
	v_readlane_b32 s51, v252, 22
	v_readlane_b32 s54, v252, 25
	v_readlane_b32 s55, v252, 26
	v_readlane_b32 s58, v252, 29
	v_readlane_b32 s59, v252, 30
